# bundle: LN exchange without acquire invalidate + NA softmax packed adds + NA bias reads from one base with ds offsets
# speedup vs baseline: 1.0085x; 1.0085x over previous
.Lna_nodma:
	s_cmp_lt_u32 s76, s81
	s_cselect_b64 s[74:75], -1, 0
	s_cmp_gt_u32 s76, s3
	s_cselect_b64 s[76:77], -1, 0
	s_or_b64 s[74:75], s[74:75], s[76:77]
	s_and_b64 vcc, exec, s[74:75]
	s_cbranch_vccnz .LBB0_249
	s_mul_hi_u32 s11, s10, 0x24924925
	s_sub_i32 s74, s10, s11
	s_lshr_b32 s74, s74, 1
	s_add_i32 s74, s74, s11
	s_lshr_b32 s11, s74, 2
	s_mul_i32 s11, s11, 0x1c000
	s_sub_i32 s11, s78, s11
	s_add_i32 s11, s11, 0
	v_add_u32_e32 v130, s11, v158
	v_add_u32_e32 v70, v130, v154
	v_add_u32_e32 v126, v130, v159
	ds_read_b128 v[174:177], v70
	ds_read_b128 v[178:181], v70 offset:4096
	v_add_u32_e32 v131, v130, v160
	ds_read_b128 v[182:185], v126
	ds_read_b128 v[186:189], v126 offset:4096
	v_add_u32_e32 v130, v130, v161
	ds_read_b128 v[190:193], v131
	ds_read_b128 v[194:197], v131 offset:4096
	ds_read_b128 v[198:201], v130
	ds_read_b128 v[202:205], v130 offset:4096
	v_readlane_b32 s76, v252, 32
	v_readlane_b32 s77, v252, 33
	v_add_u32_e32 v165, 0x205f0, v147
	s_mov_b64 s[74:75], -1
	s_and_b64 vcc, exec, s[76:77]
	s_waitcnt lgkmcnt(7)
	v_mfma_f32_32x32x16_bf16 v[82:97], v[174:177], v[98:101], v[32:47]
	s_waitcnt lgkmcnt(6)
	v_mfma_f32_32x32x16_bf16 v[66:81], v[178:181], v[98:101], v[48:63]
	s_waitcnt lgkmcnt(5)
	v_mfma_f32_32x32x16_bf16 v[82:97], v[182:185], v[102:105], v[82:97]
	s_waitcnt lgkmcnt(4)
	v_mfma_f32_32x32x16_bf16 v[66:81], v[186:189], v[102:105], v[66:81]
	s_waitcnt lgkmcnt(3)
	v_mfma_f32_32x32x16_bf16 v[82:97], v[190:193], v[106:109], v[82:97]
	s_waitcnt lgkmcnt(2)
	v_mfma_f32_32x32x16_bf16 v[66:81], v[194:197], v[106:109], v[66:81]
	s_waitcnt lgkmcnt(1)
	v_mfma_f32_32x32x16_bf16 v[82:97], v[198:201], v[110:113], v[82:97]
	s_waitcnt lgkmcnt(0)
	v_mfma_f32_32x32x16_bf16 v[66:81], v[202:205], v[110:113], v[66:81]
	s_cbranch_vccz .LBB0_238
	ds_read2_b32 v[122:123], v165 offset0:40 offset1:41
	ds_read2_b32 v[124:125], v165 offset0:42 offset1:43
	ds_read2_b32 v[126:127], v165 offset0:48 offset1:49
	ds_read2_b32 v[128:129], v165 offset0:50 offset1:51
	ds_read2_b32 v[130:131], v165 offset0:32 offset1:33
	ds_read2_b32 v[132:133], v165 offset0:56 offset1:57
	ds_read2_b32 v[134:135], v165 offset0:34 offset1:35
	ds_read2_b32 v[136:137], v165 offset0:58 offset1:59
	ds_read2_b32 v[170:171], v165 offset0:24 offset1:25
	ds_read2_b32 v[172:173], v165 offset0:26 offset1:27
	s_mov_b64 s[74:75], 0
	s_waitcnt lgkmcnt(1)
	v_mov_b32_e32 v163, v170
	s_waitcnt lgkmcnt(0)
	v_mov_b32_e32 v169, v172
	s_nop 0
	v_pk_add_f32 v[130:131], v[66:67], v[130:131]
	v_exp_f32_e32 v130, v130
	v_exp_f32_e32 v131, v131
	v_pk_add_f32 v[134:135], v[68:69], v[134:135]
	v_exp_f32_e32 v134, v134
	v_exp_f32_e32 v135, v135
	v_pk_add_f32 v[70:71], v[70:71], v[122:123]
	v_exp_f32_e32 v70, v70
	v_add_f32_e32 v170, v131, v130
	v_exp_f32_e32 v71, v71
	v_pk_add_f32 v[72:73], v[72:73], v[124:125]
	v_add_f32_e32 v170, v134, v170
	v_exp_f32_e32 v72, v72
	v_add_f32_e32 v170, v135, v170
	v_exp_f32_e32 v73, v73
	v_pk_add_f32 v[74:75], v[74:75], v[126:127]
	v_add_f32_e32 v122, v70, v170
	v_exp_f32_e32 v74, v74
	v_add_f32_e32 v122, v71, v122
	v_exp_f32_e32 v75, v75
	v_pk_add_f32 v[76:77], v[76:77], v[128:129]
	v_add_f32_e32 v122, v72, v122
	v_exp_f32_e32 v76, v76
	v_add_f32_e32 v122, v73, v122
	v_exp_f32_e32 v77, v77
	v_pk_add_f32 v[78:79], v[78:79], v[132:133]
	v_add_f32_e32 v122, v74, v122
	v_exp_f32_e32 v78, v78
	v_add_f32_e32 v122, v75, v122
	v_exp_f32_e32 v79, v79
	v_pk_add_f32 v[80:81], v[80:81], v[136:137]
	v_add_f32_e32 v122, v76, v122
	v_exp_f32_e32 v80, v80
	v_add_f32_e32 v122, v77, v122
	v_exp_f32_e32 v81, v81
	v_add_f32_e32 v123, v94, v163
	v_add_f32_e32 v122, v78, v122
	v_exp_f32_e32 v123, v123
	v_add_f32_e32 v124, v95, v171
	v_add_f32_e32 v122, v79, v122
	v_exp_f32_e32 v124, v124
	v_add_f32_e32 v125, v96, v169
	v_add_f32_e32 v126, v97, v173
	v_add_f32_e32 v122, v80, v122
	v_exp_f32_e32 v125, v125
	v_exp_f32_e32 v126, v126
	v_add_f32_e32 v122, v81, v122
	v_add_f32_e32 v122, v123, v122
	v_add_f32_e32 v122, v124, v122
	v_add_f32_e32 v122, v125, v122
	v_cvt_pk_bf16_f32 v132, v123, v124
	v_cvt_pk_bf16_f32 v133, v125, v126
	v_cvt_pk_bf16_f32 v124, v78, v79
	v_cvt_pk_bf16_f32 v125, v80, v81
	v_add_f32_e32 v163, v126, v122
	v_cvt_pk_bf16_f32 v127, v134, v135
	v_cvt_pk_bf16_f32 v122, v74, v75
	v_cvt_pk_bf16_f32 v123, v76, v77
	v_mov_b64_e32 v[136:137], v[124:125]
	v_cvt_pk_bf16_f32 v126, v130, v131
	v_cvt_pk_bf16_f32 v128, v70, v71
	v_cvt_pk_bf16_f32 v129, v72, v73
	v_mov_b64_e32 v[134:135], v[122:123]
.LBB0_238:
	v_mov_b32_e32 v130, 0
	s_andn2_b64 vcc, exec, s[74:75]
	v_mov_b32_e32 v131, v130
	s_cbranch_vccnz .LBB0_240
	s_nop 6
	ds_read2_b32 v[114:115], v165 offset0:26 offset1:27
	ds_read2_b32 v[116:117], v165 offset0:18 offset1:19
	ds_read2_b32 v[122:123], v165 offset0:32 offset1:33
	ds_read2_b32 v[124:125], v165 offset0:34 offset1:35
	ds_read2_b32 v[70:71], v165 offset1:1
	ds_read2_b32 v[72:73], v165 offset0:2 offset1:3
	ds_read2_b32 v[74:75], v165 offset0:8 offset1:9
	ds_read2_b32 v[76:77], v165 offset0:10 offset1:11
	ds_read2_b32 v[78:79], v165 offset0:16 offset1:17
	ds_read2_b32 v[80:81], v165 offset0:24 offset1:25
	s_waitcnt lgkmcnt(0)
	s_nop 0
	v_pk_add_f32 v[70:71], v[82:83], v[70:71]
	v_exp_f32_e32 v70, v70
	v_exp_f32_e32 v71, v71
	v_pk_add_f32 v[72:73], v[84:85], v[72:73]
	v_exp_f32_e32 v72, v72
	v_exp_f32_e32 v73, v73
	v_pk_add_f32 v[74:75], v[86:87], v[74:75]
	v_exp_f32_e32 v74, v74
	v_add_f32_e32 v82, v71, v70
	v_exp_f32_e32 v75, v75
	v_pk_add_f32 v[76:77], v[88:89], v[76:77]
	v_add_f32_e32 v82, v72, v82
	v_exp_f32_e32 v76, v76
	v_add_f32_e32 v82, v73, v82
	v_exp_f32_e32 v77, v77
	v_pk_add_f32 v[78:79], v[90:91], v[78:79]
	v_add_f32_e32 v82, v74, v82
	v_exp_f32_e32 v78, v78
	v_add_f32_e32 v82, v75, v82
	v_exp_f32_e32 v79, v79
	v_add_f32_e32 v83, v92, v116
	v_add_f32_e32 v82, v76, v82
	v_exp_f32_e32 v83, v83
	v_add_f32_e32 v84, v93, v117
	v_add_f32_e32 v82, v77, v82
	v_exp_f32_e32 v84, v84
	v_pk_add_f32 v[80:81], v[94:95], v[80:81]
	v_add_f32_e32 v82, v78, v82
	v_exp_f32_e32 v80, v80
	v_add_f32_e32 v82, v79, v82
	v_exp_f32_e32 v81, v81
	v_add_f32_e32 v85, v96, v114
	v_add_f32_e32 v82, v83, v82
	v_exp_f32_e32 v85, v85
	v_add_f32_e32 v86, v97, v115
	v_add_f32_e32 v82, v84, v82
	v_exp_f32_e32 v86, v86
	v_pk_add_f32 v[66:67], v[66:67], v[122:123]
	v_add_f32_e32 v82, v80, v82
	v_exp_f32_e32 v66, v66
	v_add_f32_e32 v82, v81, v82
	v_exp_f32_e32 v67, v67
	v_pk_add_f32 v[68:69], v[68:69], v[124:125]
	v_add_f32_e32 v82, v85, v82
	v_exp_f32_e32 v68, v68
	v_add_f32_e32 v82, v86, v82
	v_exp_f32_e32 v69, v69
	v_add_f32_e32 v82, v66, v82
	v_add_f32_e32 v82, v67, v82
	v_add_f32_e32 v82, v68, v82
	v_mov_b64_e32 v[136:137], v[120:121]
	v_add_f32_e32 v163, v69, v82
	v_cvt_pk_bf16_f32 v114, v70, v71
	v_cvt_pk_bf16_f32 v115, v72, v73
	v_cvt_pk_bf16_f32 v116, v74, v75
	v_cvt_pk_bf16_f32 v117, v76, v77
	v_cvt_pk_bf16_f32 v130, v78, v79
	v_cvt_pk_bf16_f32 v131, v83, v84
	v_cvt_pk_bf16_f32 v132, v80, v81
	v_cvt_pk_bf16_f32 v133, v85, v86
	v_cvt_pk_bf16_f32 v126, v66, v67
	v_cvt_pk_bf16_f32 v127, v68, v69
	v_mov_b32_e32 v128, 0
	v_mov_b64_e32 v[134:135], v[118:119]
	v_mov_b32_e32 v122, v118
	v_mov_b32_e32 v123, v119
	v_mov_b32_e32 v124, v120
	v_mov_b32_e32 v125, v121
	v_mov_b32_e32 v129, 0
